# first-barrier census: 16 counter loads in flight together; final-norm epilogue: 8 row-statistic loads batched (one round trip instead of eight)
# speedup vs baseline: 1.0111x; 1.0111x over previous
; __device__ __forceinline__ unsigned xb_ld(unsigned* p)              { return __hip_atomic_load(p, __ATOMIC_RELAXED, __HIP_MEMORY_SCOPE_AGENT); }
; __device__ __forceinline__ void xcd_barrier_complete(unsigned* bar, unsigned x, unsigned& nloc, unsigned& nx) {
;     ...
;     for (;;) {
;         sum = 0u; cnt = 0u; mine = 0u;
; #pragma unroll
;         for (unsigned j = 0; j < 16; ++j) { const unsigned c = xb_ld(&bar[XB_XCNT(j)]); sum += c; cnt += (c > 0u) ? 1u : 0u; mine = (j == x) ? c : mine; }
;         if (sum == G) break;
;         __builtin_amdgcn_s_sleep(1);
;         if ((++sp & 255u) == 0u) { if (xb_ld(&bar[XB_TMO])) break; if (sp > XB_SPIN_CAP) { atomicAdd(&bar[XB_TMO], 1u); break; } }
;     }
.LBB0_26:
	v_readlane_b32 s10, v251, 8
	v_readlane_b32 s11, v251, 9
	s_mov_b64 s[16:17], -1
	s_waitcnt lgkmcnt(0)
	s_nop 3
	global_load_dword v0, v1, s[10:11] sc1
	v_readlane_b32 s10, v251, 10
	v_readlane_b32 s11, v251, 11
	s_nop 4
	global_load_dword v2, v1, s[10:11] sc1
	v_readlane_b32 s10, v251, 12
	v_readlane_b32 s11, v251, 13
	s_nop 4
	global_load_dword v3, v1, s[10:11] sc1
	v_readlane_b32 s10, v251, 14
	v_readlane_b32 s11, v251, 15
	s_nop 4
	global_load_dword v4, v1, s[10:11] sc1
	v_readlane_b32 s10, v251, 16
	v_readlane_b32 s11, v251, 17
	s_nop 4
	global_load_dword v5, v1, s[10:11] sc1
	v_readlane_b32 s10, v251, 18
	v_readlane_b32 s11, v251, 19
	s_nop 4
	global_load_dword v6, v1, s[10:11] sc1
	v_readlane_b32 s10, v251, 20
	v_readlane_b32 s11, v251, 21
	s_nop 4
	global_load_dword v7, v1, s[10:11] sc1
	v_readlane_b32 s10, v251, 22
	v_readlane_b32 s11, v251, 23
	s_nop 4
	global_load_dword v8, v1, s[10:11] sc1
	v_readlane_b32 s10, v251, 24
	v_readlane_b32 s11, v251, 25
	s_nop 4
	global_load_dword v9, v1, s[10:11] sc1
	v_readlane_b32 s10, v251, 26
	v_readlane_b32 s11, v251, 27
	s_nop 4
	global_load_dword v10, v1, s[10:11] sc1
	v_readlane_b32 s10, v251, 28
	v_readlane_b32 s11, v251, 29
	s_nop 4
	global_load_dword v11, v1, s[10:11] sc1
	v_readlane_b32 s10, v251, 30
	v_readlane_b32 s11, v251, 31
	s_nop 4
	global_load_dword v12, v1, s[10:11] sc1
	v_readlane_b32 s10, v251, 32
	v_readlane_b32 s11, v251, 33
	s_nop 4
	global_load_dword v13, v1, s[10:11] sc1
	v_readlane_b32 s10, v251, 34
	v_readlane_b32 s11, v251, 35
	s_nop 4
	global_load_dword v14, v1, s[10:11] sc1
	v_readlane_b32 s10, v251, 36
	v_readlane_b32 s11, v251, 37
	s_nop 4
	global_load_dword v15, v1, s[10:11] sc1
	v_readlane_b32 s10, v251, 38
	v_readlane_b32 s11, v251, 39
	s_nop 4
	global_load_dword v16, v1, s[10:11] sc1
	s_mov_b64 s[10:11], -1
	s_waitcnt vmcnt(0)
	v_add_u32_e32 v17, v2, v0
	v_add_u32_e32 v17, v17, v3
	v_add_u32_e32 v17, v17, v4
	v_add_u32_e32 v17, v17, v5
	v_add_u32_e32 v17, v17, v6
	v_add_u32_e32 v17, v17, v7
	v_add_u32_e32 v17, v17, v8
	v_add_u32_e32 v17, v17, v9
	v_add_u32_e32 v17, v17, v10
	v_add_u32_e32 v17, v17, v11
	v_add_u32_e32 v17, v17, v12
	v_add_u32_e32 v17, v17, v13
	v_add_u32_e32 v17, v17, v14
	v_add_u32_e32 v17, v17, v15
	v_add_u32_e32 v17, v17, v16
	v_cmp_eq_u32_e32 vcc, s26, v17
	s_cbranch_vccnz .LBB0_25
	s_and_b32 s10, s3, 0xff
	s_cmp_eq_u32 s10, 0
	s_mov_b64 s[10:11], -1
	s_mov_b64 s[18:19], -1
	s_sleep 1
	s_cbranch_scc0 .LBB0_30
	v_readlane_b32 s10, v251, 6
	v_readlane_b32 s11, v251, 7
	s_nop 4
	global_load_dword v17, v1, s[10:11] sc1
	s_waitcnt vmcnt(0)
	v_cmp_eq_u32_e32 vcc, 0, v17
	s_cbranch_vccnz .LBB0_32
	s_mov_b64 s[18:19], 0
	s_mov_b64 s[10:11], -1

;     __device__ __forceinline__ void operator()(const f32x4 (&acc_)[2][2][4][2], const Unit& u, int wr, int wc, int fr, int fq, const float (&)[8]) const {
;     ...
;         f32x4 gv[2][2];
; #pragma unroll
;         for (int bj = 0; bj < 2; ++bj) { gv[bj][0] = *(const f32x4*)(g + col0 + bj * 128); gv[bj][1] = *(const f32x4*)(g + col0 + bj * 128 + 4); }
; #pragma unroll
;         for (int ai = 0; ai < 2; ++ai)
; #pragma unroll
;             for (int m = 0; m < 4; ++m) { const int row = row0 + ai * 128 + m * 16; const size_t ro = (size_t)row * DM + col0;
;                 const float r = rsqrtf(__hip_atomic_load(RS + row, __ATOMIC_RELAXED, __HIP_MEMORY_SCOPE_AGENT) * (1.f / 1024.f) + 1e-6f);
; #pragma unroll
;                 for (int bj = 0; bj < 2; ++bj) { const size_t p = ro + bj * 128;
;                     *(f32x4*)(Out + p) = acc[ai][bj][m][0] * r * gv[bj][0]; *(f32x4*)(Out + p + 4) = acc[ai][bj][m][1] * r * gv[bj][1]; } }
.LBB0_453:
	s_or_b64 exec, exec, s[16:17]
	v_lshl_or_b32 v130, s86, 8, v169
	v_ashrrev_i32_e32 v131, 31, v130
	v_readlane_b32 s16, v251, 0
	v_lshlrev_b64 v[164:165], 2, v[130:131]
	v_readlane_b32 s17, v251, 1
	s_barrier
	s_nop 0
	v_lshl_add_u64 v[134:135], s[16:17], 0, v[164:165]
	global_load_dwordx4 v[138:141], v[134:135], off offset:16
	global_load_dwordx4 v[142:145], v[134:135], off
	global_load_dwordx4 v[130:133], v[134:135], off offset:528
	s_nop 0
	global_load_dwordx4 v[134:137], v[134:135], off offset:512
	s_nop 0
	global_load_dword v160, v[158:159], off sc1
	global_load_dword v202, v[158:159], off offset:64 sc1
	global_load_dword v203, v[158:159], off offset:128 sc1
	global_load_dword v204, v[158:159], off offset:192 sc1
	global_load_dword v205, v[158:159], off offset:512 sc1
	global_load_dword v206, v[158:159], off offset:576 sc1
	global_load_dword v207, v[158:159], off offset:640 sc1
	global_load_dword v208, v[158:159], off offset:704 sc1
	v_readlane_b32 s18, v251, 2
	v_readlane_b32 s19, v251, 3
	s_mov_b32 s3, 0x80000
	s_mov_b64 s[14:15], 0x80000
	s_waitcnt vmcnt(0)
	v_fmamk_f32 v160, v160, 0x3a800000, v189
	v_cmp_gt_f32_e32 vcc, s27, v160
	v_mul_f32_e32 v161, 0x4b800000, v160
	s_nop 0
	v_cndmask_b32_e32 v160, v160, v161, vcc
	v_rsq_f32_e32 v160, v160
	s_nop 0
	v_mul_f32_e32 v161, 0x45800000, v160
	v_cndmask_b32_e32 v176, v160, v161, vcc
	v_pk_mul_f32 v[160:161], v[58:59], v[176:177] op_sel_hi:[1,0]
	v_pk_mul_f32 v[172:173], v[60:61], v[176:177] op_sel_hi:[1,0]
	s_nop 0
	v_pk_mul_f32 v[174:175], v[144:145], v[172:173]
	v_pk_mul_f32 v[172:173], v[142:143], v[160:161]
	v_lshlrev_b64 v[160:161], 12, v[162:163]
	v_lshl_add_u64 v[160:161], s[18:19], 0, v[160:161]
	v_lshl_add_u64 v[160:161], v[160:161], 0, v[164:165]
	global_store_dwordx4 v[160:161], v[172:175], off
	s_nop 1
	v_pk_mul_f32 v[172:173], v[50:51], v[176:177] op_sel_hi:[1,0]
	v_pk_mul_f32 v[174:175], v[52:53], v[176:177] op_sel_hi:[1,0]
	v_pk_mul_f32 v[172:173], v[138:139], v[172:173]
	v_pk_mul_f32 v[174:175], v[140:141], v[174:175]
	global_store_dwordx4 v[160:161], v[172:175], off offset:16
	s_nop 1
	v_pk_mul_f32 v[172:173], v[6:7], v[176:177] op_sel_hi:[1,0]
	v_pk_mul_f32 v[174:175], v[8:9], v[176:177] op_sel_hi:[1,0]
	v_pk_mul_f32 v[172:173], v[134:135], v[172:173]
	v_pk_mul_f32 v[174:175], v[136:137], v[174:175]
	global_store_dwordx4 v[160:161], v[172:175], off offset:512
	s_nop 1
	v_pk_mul_f32 v[172:173], v[2:3], v[176:177] op_sel_hi:[1,0]
	v_pk_mul_f32 v[174:175], v[4:5], v[176:177] op_sel_hi:[1,0]
	v_pk_mul_f32 v[172:173], v[130:131], v[172:173]
	v_pk_mul_f32 v[174:175], v[132:133], v[174:175]
	global_store_dwordx4 v[160:161], v[172:175], off offset:528
	s_nop 1
	v_mov_b32_e32 v163, v202
	v_or_b32_e32 v176, 16, v162
	v_ashrrev_i32_e32 v177, 31, v176
	v_lshlrev_b64 v[176:177], 12, v[176:177]
	v_lshl_add_u64 v[176:177], s[18:19], 0, v[176:177]
	v_lshl_add_u64 v[176:177], v[176:177], 0, v[164:165]
	v_fmamk_f32 v163, v163, 0x3a800000, v189
	v_cmp_gt_f32_e32 vcc, s27, v163
	v_mul_f32_e32 v171, 0x4b800000, v163
	s_nop 0
	v_cndmask_b32_e32 v163, v163, v171, vcc
	v_rsq_f32_e32 v163, v163
	s_nop 0
	v_mul_f32_e32 v171, 0x45800000, v163
	v_cndmask_b32_e32 v182, v163, v171, vcc
	v_pk_mul_f32 v[172:173], v[14:15], v[182:183] op_sel_hi:[1,0]
	v_pk_mul_f32 v[174:175], v[16:17], v[182:183] op_sel_hi:[1,0]
	v_pk_mul_f32 v[172:173], v[142:143], v[172:173]
	v_pk_mul_f32 v[174:175], v[144:145], v[174:175]
	global_store_dwordx4 v[176:177], v[172:175], off
	s_nop 1
	v_pk_mul_f32 v[172:173], v[10:11], v[182:183] op_sel_hi:[1,0]
	v_pk_mul_f32 v[174:175], v[12:13], v[182:183] op_sel_hi:[1,0]
	v_pk_mul_f32 v[172:173], v[138:139], v[172:173]
	v_pk_mul_f32 v[174:175], v[140:141], v[174:175]
	global_store_dwordx4 v[176:177], v[172:175], off offset:16
	s_nop 1
	v_pk_mul_f32 v[172:173], v[22:23], v[182:183] op_sel_hi:[1,0]
	v_pk_mul_f32 v[174:175], v[24:25], v[182:183] op_sel_hi:[1,0]
	v_pk_mul_f32 v[172:173], v[134:135], v[172:173]
	v_pk_mul_f32 v[174:175], v[136:137], v[174:175]
	global_store_dwordx4 v[176:177], v[172:175], off offset:512
	s_nop 1
	v_pk_mul_f32 v[172:173], v[18:19], v[182:183] op_sel_hi:[1,0]
	v_pk_mul_f32 v[174:175], v[20:21], v[182:183] op_sel_hi:[1,0]
	v_pk_mul_f32 v[172:173], v[130:131], v[172:173]
	v_pk_mul_f32 v[174:175], v[132:133], v[174:175]
	global_store_dwordx4 v[176:177], v[172:175], off offset:528
	s_nop 1
	v_mov_b32_e32 v163, v203
	v_or_b32_e32 v176, 32, v162
	v_ashrrev_i32_e32 v177, 31, v176
	v_lshlrev_b64 v[176:177], 12, v[176:177]
	v_lshl_add_u64 v[176:177], s[18:19], 0, v[176:177]
	v_lshl_add_u64 v[176:177], v[176:177], 0, v[164:165]
	v_or_b32_e32 v162, 48, v162
	v_fmamk_f32 v163, v163, 0x3a800000, v189
	v_cmp_gt_f32_e32 vcc, s27, v163
	v_mul_f32_e32 v171, 0x4b800000, v163
	s_nop 0
	v_cndmask_b32_e32 v163, v163, v171, vcc
	v_rsq_f32_e32 v163, v163
	s_nop 0
	v_mul_f32_e32 v171, 0x45800000, v163
	v_cndmask_b32_e32 v182, v163, v171, vcc
	v_pk_mul_f32 v[172:173], v[30:31], v[182:183] op_sel_hi:[1,0]
	v_pk_mul_f32 v[174:175], v[32:33], v[182:183] op_sel_hi:[1,0]
	v_pk_mul_f32 v[172:173], v[142:143], v[172:173]
	v_pk_mul_f32 v[174:175], v[144:145], v[174:175]
	global_store_dwordx4 v[176:177], v[172:175], off
	v_ashrrev_i32_e32 v163, 31, v162
	v_lshlrev_b64 v[162:163], 12, v[162:163]
	v_pk_mul_f32 v[172:173], v[26:27], v[182:183] op_sel_hi:[1,0]
	v_pk_mul_f32 v[174:175], v[28:29], v[182:183] op_sel_hi:[1,0]
	v_pk_mul_f32 v[172:173], v[138:139], v[172:173]
	v_pk_mul_f32 v[174:175], v[140:141], v[174:175]
	global_store_dwordx4 v[176:177], v[172:175], off offset:16
	v_lshl_add_u64 v[162:163], s[18:19], 0, v[162:163]
	s_nop 0
	v_pk_mul_f32 v[172:173], v[38:39], v[182:183] op_sel_hi:[1,0]
;     __device__ __forceinline__ void operator()(const f32x4 (&acc_)[2][2][4][2], const Unit& u, int wr, int wc, int fr, int fq, const float (&)[8]) const {
;     ...
; #pragma unroll
;         for (int ai = 0; ai < 2; ++ai)
; #pragma unroll
;             for (int m = 0; m < 4; ++m) { const int row = row0 + ai * 128 + m * 16; const size_t ro = (size_t)row * DM + col0;
;                 const float r = rsqrtf(__hip_atomic_load(RS + row, __ATOMIC_RELAXED, __HIP_MEMORY_SCOPE_AGENT) * (1.f / 1024.f) + 1e-6f);
; #pragma unroll
;                 for (int bj = 0; bj < 2; ++bj) { const size_t p = ro + bj * 128;
;                     *(f32x4*)(Out + p) = acc[ai][bj][m][0] * r * gv[bj][0]; *(f32x4*)(Out + p + 4) = acc[ai][bj][m][1] * r * gv[bj][1]; } }
	v_pk_mul_f32 v[174:175], v[40:41], v[182:183] op_sel_hi:[1,0]
	v_pk_mul_f32 v[172:173], v[134:135], v[172:173]
	v_pk_mul_f32 v[174:175], v[136:137], v[174:175]
	global_store_dwordx4 v[176:177], v[172:175], off offset:512
	s_nop 1
	v_pk_mul_f32 v[172:173], v[34:35], v[182:183] op_sel_hi:[1,0]
	v_pk_mul_f32 v[174:175], v[36:37], v[182:183] op_sel_hi:[1,0]
	v_pk_mul_f32 v[172:173], v[130:131], v[172:173]
	v_pk_mul_f32 v[174:175], v[132:133], v[174:175]
	global_store_dwordx4 v[176:177], v[172:175], off offset:528
	s_nop 1
	v_mov_b32_e32 v171, v204
	v_lshl_add_u64 v[182:183], v[162:163], 0, v[164:165]
	v_fmamk_f32 v171, v171, 0x3a800000, v189
	v_cmp_gt_f32_e32 vcc, s27, v171
	v_mul_f32_e32 v172, 0x4b800000, v171
	s_nop 0
	v_cndmask_b32_e32 v171, v171, v172, vcc
	v_rsq_f32_e32 v171, v171
	s_nop 0
	v_mul_f32_e32 v172, 0x45800000, v171
	v_cndmask_b32_e32 v176, v171, v172, vcc
	v_pk_mul_f32 v[162:163], v[42:43], v[176:177] op_sel_hi:[1,0]
	v_pk_mul_f32 v[164:165], v[44:45], v[176:177] op_sel_hi:[1,0]
	v_pk_mul_f32 v[162:163], v[138:139], v[162:163]
	v_pk_mul_f32 v[164:165], v[140:141], v[164:165]
	global_store_dwordx4 v[182:183], v[162:165], off offset:16
	v_pk_mul_f32 v[172:173], v[46:47], v[176:177] op_sel_hi:[1,0]
	v_pk_mul_f32 v[174:175], v[48:49], v[176:177] op_sel_hi:[1,0]
	v_pk_mul_f32 v[162:163], v[62:63], v[176:177] op_sel_hi:[1,0]
	v_pk_mul_f32 v[164:165], v[64:65], v[176:177] op_sel_hi:[1,0]
	v_pk_mul_f32 v[162:163], v[134:135], v[162:163]
	v_pk_mul_f32 v[164:165], v[136:137], v[164:165]
	global_store_dwordx4 v[182:183], v[162:165], off offset:512
	v_pk_mul_f32 v[174:175], v[144:145], v[174:175]
	v_pk_mul_f32 v[172:173], v[142:143], v[172:173]
	v_pk_mul_f32 v[162:163], v[54:55], v[176:177] op_sel_hi:[1,0]
	v_pk_mul_f32 v[164:165], v[56:57], v[176:177] op_sel_hi:[1,0]
	v_pk_mul_f32 v[162:163], v[130:131], v[162:163]
	v_pk_mul_f32 v[164:165], v[132:133], v[164:165]
	global_store_dwordx4 v[182:183], v[172:175], off
	global_store_dwordx4 v[182:183], v[162:165], off offset:528
	s_nop 1
	v_mov_b32_e32 v162, v205
	v_lshl_add_u64 v[174:175], v[160:161], 0, s[14:15]
	s_mov_b64 s[14:15], 0x90000
	v_fmamk_f32 v162, v162, 0x3a800000, v189
	v_cmp_gt_f32_e32 vcc, s27, v162
	v_mul_f32_e32 v163, 0x4b800000, v162
	s_nop 0
	v_cndmask_b32_e32 v162, v162, v163, vcc
	v_rsq_f32_e32 v162, v162
	s_nop 0
	v_mul_f32_e32 v163, 0x45800000, v162
	v_cndmask_b32_e32 v172, v162, v163, vcc
	v_pk_mul_f32 v[162:163], v[70:71], v[172:173] op_sel_hi:[1,0]
	v_pk_mul_f32 v[164:165], v[72:73], v[172:173] op_sel_hi:[1,0]
	v_add_co_u32_e32 v176, vcc, s3, v160
	v_pk_mul_f32 v[164:165], v[144:145], v[164:165]
	v_pk_mul_f32 v[162:163], v[142:143], v[162:163]
	v_addc_co_u32_e32 v177, vcc, 0, v161, vcc
	global_store_dwordx4 v[176:177], v[162:165], off
	s_mov_b32 s3, 0x90000
	s_nop 0
	v_pk_mul_f32 v[162:163], v[66:67], v[172:173] op_sel_hi:[1,0]
	v_pk_mul_f32 v[164:165], v[68:69], v[172:173] op_sel_hi:[1,0]
	v_pk_mul_f32 v[162:163], v[138:139], v[162:163]
	v_pk_mul_f32 v[164:165], v[140:141], v[164:165]
	global_store_dwordx4 v[174:175], v[162:165], off offset:16
	s_nop 1
	v_pk_mul_f32 v[162:163], v[78:79], v[172:173] op_sel_hi:[1,0]
	v_pk_mul_f32 v[164:165], v[80:81], v[172:173] op_sel_hi:[1,0]
	v_pk_mul_f32 v[162:163], v[134:135], v[162:163]
	v_pk_mul_f32 v[164:165], v[136:137], v[164:165]
	global_store_dwordx4 v[174:175], v[162:165], off offset:512
	s_nop 1
	v_pk_mul_f32 v[162:163], v[74:75], v[172:173] op_sel_hi:[1,0]
	v_pk_mul_f32 v[164:165], v[76:77], v[172:173] op_sel_hi:[1,0]
	v_pk_mul_f32 v[162:163], v[130:131], v[162:163]
	v_pk_mul_f32 v[164:165], v[132:133], v[164:165]
	global_store_dwordx4 v[174:175], v[162:165], off offset:528
	s_nop 1
	v_mov_b32_e32 v162, v206
	v_lshl_add_u64 v[174:175], v[160:161], 0, s[14:15]
	s_mov_b64 s[14:15], 0xa0000
	v_fmamk_f32 v162, v162, 0x3a800000, v189
	v_cmp_gt_f32_e32 vcc, s27, v162
	v_mul_f32_e32 v163, 0x4b800000, v162
	s_nop 0
	v_cndmask_b32_e32 v162, v162, v163, vcc
	v_rsq_f32_e32 v162, v162
	s_nop 0
	v_mul_f32_e32 v163, 0x45800000, v162
	v_cndmask_b32_e32 v172, v162, v163, vcc
	v_pk_mul_f32 v[162:163], v[86:87], v[172:173] op_sel_hi:[1,0]
	v_pk_mul_f32 v[164:165], v[88:89], v[172:173] op_sel_hi:[1,0]
	v_add_co_u32_e32 v176, vcc, s3, v160
	v_pk_mul_f32 v[164:165], v[144:145], v[164:165]
	v_pk_mul_f32 v[162:163], v[142:143], v[162:163]
	v_addc_co_u32_e32 v177, vcc, 0, v161, vcc
	global_store_dwordx4 v[176:177], v[162:165], off
	s_mov_b32 s3, 0xa0000
	s_nop 0
	v_pk_mul_f32 v[162:163], v[82:83], v[172:173] op_sel_hi:[1,0]
	v_pk_mul_f32 v[164:165], v[84:85], v[172:173] op_sel_hi:[1,0]
	v_pk_mul_f32 v[162:163], v[138:139], v[162:163]
	v_pk_mul_f32 v[164:165], v[140:141], v[164:165]
	global_store_dwordx4 v[174:175], v[162:165], off offset:16
	s_nop 1
	v_pk_mul_f32 v[162:163], v[94:95], v[172:173] op_sel_hi:[1,0]
	v_pk_mul_f32 v[164:165], v[96:97], v[172:173] op_sel_hi:[1,0]
	v_pk_mul_f32 v[162:163], v[134:135], v[162:163]
	v_pk_mul_f32 v[164:165], v[136:137], v[164:165]
	global_store_dwordx4 v[174:175], v[162:165], off offset:512
	s_nop 1
	v_pk_mul_f32 v[162:163], v[90:91], v[172:173] op_sel_hi:[1,0]
	v_pk_mul_f32 v[164:165], v[92:93], v[172:173] op_sel_hi:[1,0]
	v_pk_mul_f32 v[162:163], v[130:131], v[162:163]
	v_pk_mul_f32 v[164:165], v[132:133], v[164:165]
	global_store_dwordx4 v[174:175], v[162:165], off offset:528
	s_nop 1
	v_mov_b32_e32 v162, v207
	v_lshl_add_u64 v[174:175], v[160:161], 0, s[14:15]
	s_mov_b64 s[14:15], 0xb0000
	v_fmamk_f32 v162, v162, 0x3a800000, v189
	v_cmp_gt_f32_e32 vcc, s27, v162
	v_mul_f32_e32 v163, 0x4b800000, v162
	s_nop 0
	v_cndmask_b32_e32 v162, v162, v163, vcc
	v_rsq_f32_e32 v162, v162
	s_nop 0
;     __device__ void init(int M, int N, int G_, int c_, int off) { nM = M / 256; nN = N / 256; nwg = nM * nN; G = G_; c = c_ - off; if (c < 0) c += G_; }
;     __device__ __forceinline__ void init(f32x4 (&acc)[2][2][4][2], const Unit& u, int wr, int wc, int fr, int fq) const {
;         const int row0 = u.pm * 256 + wr * 64 + fr, col0 = u.pn * 256 + wc * 32 + 8 * fq;
; #pragma unroll
;         for (int ai = 0; ai < 2; ++ai)
; #pragma unroll
;             for (int m = 0; m < 4; ++m)
; #pragma unroll
;                 for (int bj = 0; bj < 2; ++bj) { const size_t p = (size_t)(row0 + ai * 128 + m * 16) * DM + col0 + bj * 128;
;                     if (Xin32) { acc[ai][bj][m][0] = *(const f32x4*)(Xin32 + p); acc[ai][bj][m][1] = *(const f32x4*)(Xin32 + p + 4); }
;                     else { acc[ai][bj][m][0] = __builtin_bit_cast(f32x4, *(const u32x4*)(HiIn + p)); acc[ai][bj][m][1] = __builtin_bit_cast(f32x4, *(const u32x4*)(LoIn + p)); } }
;     __device__ __forceinline__ void operator()(const f32x4 (&acc_)[2][2][4][2], const Unit& u, int wr, int wc, int fr, int fq, const float (&)[8]) const {
;     ...
; #pragma unroll
;         for (int ai = 0; ai < 2; ++ai)
; #pragma unroll
;             for (int m = 0; m < 4; ++m) { const int row = row0 + ai * 128 + m * 16; const size_t ro = (size_t)row * DM + col0;
;                 const float r = rsqrtf(__hip_atomic_load(RS + row, __ATOMIC_RELAXED, __HIP_MEMORY_SCOPE_AGENT) * (1.f / 1024.f) + 1e-6f);
; #pragma unroll
;                 for (int bj = 0; bj < 2; ++bj) { const size_t p = ro + bj * 128;
;                     *(f32x4*)(Out + p) = acc[ai][bj][m][0] * r * gv[bj][0]; *(f32x4*)(Out + p + 4) = acc[ai][bj][m][1] * r * gv[bj][1]; } }
	v_mul_f32_e32 v163, 0x45800000, v162
	v_cndmask_b32_e32 v172, v162, v163, vcc
	v_pk_mul_f32 v[162:163], v[102:103], v[172:173] op_sel_hi:[1,0]
	v_pk_mul_f32 v[164:165], v[104:105], v[172:173] op_sel_hi:[1,0]
	v_add_co_u32_e32 v176, vcc, s3, v160
	v_pk_mul_f32 v[164:165], v[144:145], v[164:165]
	v_pk_mul_f32 v[162:163], v[142:143], v[162:163]
	v_addc_co_u32_e32 v177, vcc, 0, v161, vcc
	global_store_dwordx4 v[176:177], v[162:165], off
	s_mov_b32 s3, 0xb0000
	s_nop 0
	v_pk_mul_f32 v[162:163], v[98:99], v[172:173] op_sel_hi:[1,0]
	v_pk_mul_f32 v[164:165], v[100:101], v[172:173] op_sel_hi:[1,0]
	v_pk_mul_f32 v[162:163], v[138:139], v[162:163]
	v_pk_mul_f32 v[164:165], v[140:141], v[164:165]
	global_store_dwordx4 v[174:175], v[162:165], off offset:16
	s_nop 1
	v_pk_mul_f32 v[162:163], v[110:111], v[172:173] op_sel_hi:[1,0]
	v_pk_mul_f32 v[164:165], v[112:113], v[172:173] op_sel_hi:[1,0]
	v_pk_mul_f32 v[162:163], v[134:135], v[162:163]
	v_pk_mul_f32 v[164:165], v[136:137], v[164:165]
	global_store_dwordx4 v[174:175], v[162:165], off offset:512
	s_nop 1
	v_pk_mul_f32 v[162:163], v[106:107], v[172:173] op_sel_hi:[1,0]
	v_pk_mul_f32 v[164:165], v[108:109], v[172:173] op_sel_hi:[1,0]
	v_pk_mul_f32 v[162:163], v[130:131], v[162:163]
	v_pk_mul_f32 v[164:165], v[132:133], v[164:165]
	global_store_dwordx4 v[174:175], v[162:165], off offset:528
	s_nop 1
	v_mov_b32_e32 v158, v208
	v_fmamk_f32 v158, v158, 0x3a800000, v189
	v_cmp_gt_f32_e32 vcc, s27, v158
	v_mul_f32_e32 v159, 0x4b800000, v158
	s_nop 0
	v_cndmask_b32_e32 v158, v158, v159, vcc
	v_rsq_f32_e32 v158, v158
	s_nop 0
	v_mul_f32_e32 v159, 0x45800000, v158
	v_cndmask_b32_e32 v158, v158, v159, vcc
	v_pk_mul_f32 v[162:163], v[118:119], v[158:159] op_sel_hi:[1,0]
	v_pk_mul_f32 v[164:165], v[120:121], v[158:159] op_sel_hi:[1,0]
	v_pk_mul_f32 v[142:143], v[142:143], v[162:163]
	v_lshl_add_u64 v[162:163], v[160:161], 0, s[14:15]
	v_add_co_u32_e32 v160, vcc, s3, v160
	v_pk_mul_f32 v[144:145], v[144:145], v[164:165]
	s_nop 0
	v_addc_co_u32_e32 v161, vcc, 0, v161, vcc
	global_store_dwordx4 v[160:161], v[142:145], off
	s_and_b64 vcc, exec, s[42:43]
	s_nop 0
	v_pk_mul_f32 v[142:143], v[114:115], v[158:159] op_sel_hi:[1,0]
	v_pk_mul_f32 v[144:145], v[116:117], v[158:159] op_sel_hi:[1,0]
	v_pk_mul_f32 v[138:139], v[138:139], v[142:143]
	v_pk_mul_f32 v[140:141], v[140:141], v[144:145]
	global_store_dwordx4 v[162:163], v[138:141], off offset:16
	s_nop 1
	v_pk_mul_f32 v[138:139], v[126:127], v[158:159] op_sel_hi:[1,0]
	v_pk_mul_f32 v[140:141], v[128:129], v[158:159] op_sel_hi:[1,0]
	v_pk_mul_f32 v[134:135], v[134:135], v[138:139]
	v_pk_mul_f32 v[136:137], v[136:137], v[140:141]
	global_store_dwordx4 v[162:163], v[134:137], off offset:512
	s_nop 1
	v_pk_mul_f32 v[134:135], v[122:123], v[158:159] op_sel_hi:[1,0]
	v_pk_mul_f32 v[136:137], v[124:125], v[158:159] op_sel_hi:[1,0]
	v_pk_mul_f32 v[130:131], v[130:131], v[134:135]
	v_pk_mul_f32 v[132:133], v[132:133], v[136:137]
	global_store_dwordx4 v[162:163], v[130:133], off offset:528
	s_cbranch_vccnz .LBB0_408
	v_lshl_add_u32 v42, s92, 8, v167
	v_lshl_or_b32 v44, s91, 8, v169
	v_ashrrev_i32_e32 v43, 31, v42
	v_ashrrev_i32_e32 v45, 31, v44
	v_lshlrev_b64 v[2:3], 10, v[42:43]
	v_lshl_add_u64 v[58:59], v[2:3], 0, v[44:45]
	v_lshlrev_b64 v[2:3], 1, v[58:59]
	v_lshl_add_u64 v[8:9], v[58:59], 2, s[10:11]
	v_lshl_add_u64 v[6:7], s[50:51], 0, v[2:3]
	v_lshl_add_u64 v[10:11], v[8:9], 0, 16
	v_cndmask_b32_e64 v52, v10, v6, s[36:37]
	v_or_b32_e32 v10, 16, v42
	v_or_b32_e32 v26, 32, v42
	v_or_b32_e32 v42, 48, v42
	v_ashrrev_i32_e32 v43, 31, v42
	v_lshlrev_b64 v[42:43], 10, v[42:43]
	v_readlane_b32 s14, v252, 16
	v_cndmask_b32_e64 v53, v11, v7, s[36:37]
	v_ashrrev_i32_e32 v11, 31, v10
	v_ashrrev_i32_e32 v27, 31, v26
	v_lshl_add_u64 v[42:43], v[42:43], 0, v[44:45]
	v_readlane_b32 s15, v252, 17
	v_lshlrev_b64 v[10:11], 10, v[10:11]
	v_lshlrev_b64 v[26:27], 10, v[26:27]
	v_lshlrev_b64 v[54:55], 1, v[42:43]
	v_lshl_add_u64 v[60:61], v[42:43], 2, s[10:11]
	s_mov_b64 s[16:17], 0x100
	s_mov_b64 s[18:19], 0x200
	s_mov_b64 s[20:21], 0x210
	v_lshl_add_u64 v[10:11], v[10:11], 0, v[44:45]
	v_lshl_add_u64 v[26:27], v[26:27], 0, v[44:45]
	v_lshl_add_u64 v[44:45], s[14:15], 0, v[54:55]
	v_lshl_add_u64 v[56:57], s[50:51], 0, v[54:55]
	v_lshl_add_u64 v[42:43], v[60:61], 0, 16
	v_cndmask_b32_e64 v45, v61, v45, s[36:37]
	v_cndmask_b32_e64 v44, v60, v44, s[36:37]
	v_cndmask_b32_e64 v43, v43, v57, s[36:37]
	v_cndmask_b32_e64 v42, v42, v56, s[36:37]
	v_lshl_add_u64 v[56:57], v[56:57], 0, s[16:17]
	v_lshl_add_u64 v[62:63], v[60:61], 0, s[18:19]
	v_lshl_add_u64 v[60:61], v[60:61], 0, s[20:21]
	s_mov_b64 s[22:23], 0x20000
	v_cndmask_b32_e64 v57, v61, v57, s[36:37]
	v_cndmask_b32_e64 v56, v60, v56, s[36:37]
	v_lshl_add_u64 v[60:61], v[58:59], 0, s[22:23]
	v_lshlrev_b64 v[18:19], 1, v[10:11]
	v_lshl_add_u64 v[22:23], v[10:11], 2, s[10:11]
	v_lshlrev_b64 v[34:35], 1, v[26:27]
	v_lshl_add_u64 v[38:39], v[26:27], 2, s[10:11]
	v_lshlrev_b64 v[74:75], 1, v[60:61]
	v_lshl_add_u64 v[60:61], v[60:61], 2, s[10:11]
	v_lshl_add_u64 v[4:5], s[14:15], 0, v[2:3]
	v_or_b32_e32 v2, 0x100, v2
	v_lshl_add_u64 v[12:13], s[14:15], 0, v[18:19]
	v_lshl_add_u64 v[20:21], s[50:51], 0, v[18:19]
	v_lshl_add_u64 v[10:11], v[22:23], 0, 16
	v_or_b32_e32 v18, 0x100, v18
	v_lshl_add_u64 v[28:29], s[14:15], 0, v[34:35]
	v_lshl_add_u64 v[36:37], s[50:51], 0, v[34:35]
	v_lshl_add_u64 v[26:27], v[38:39], 0, 16
	v_or_b32_e32 v34, 0x100, v34
	v_or_b32_e32 v54, 0x100, v54
	v_lshl_add_u64 v[66:67], s[14:15], 0, v[74:75]
	v_lshl_add_u64 v[76:77], s[50:51], 0, v[74:75]
	v_lshl_add_u64 v[68:69], v[60:61], 0, 16
	v_or_b32_e32 v74, 0x100, v74
;     __device__ void init(int M, int N, int G_, int c_, int off) { nM = M / 256; nN = N / 256; nwg = nM * nN; G = G_; c = c_ - off; if (c < 0) c += G_; }
;     __device__ __forceinline__ void init(f32x4 (&acc)[2][2][4][2], const Unit& u, int wr, int wc, int fr, int fq) const {
;         const int row0 = u.pm * 256 + wr * 64 + fr, col0 = u.pn * 256 + wc * 32 + 8 * fq;
; #pragma unroll
;         for (int ai = 0; ai < 2; ++ai)
; #pragma unroll
;             for (int m = 0; m < 4; ++m)
; #pragma unroll
;                 for (int bj = 0; bj < 2; ++bj) { const size_t p = (size_t)(row0 + ai * 128 + m * 16) * DM + col0 + bj * 128;
;                     if (Xin32) { acc[ai][bj][m][0] = *(const f32x4*)(Xin32 + p); acc[ai][bj][m][1] = *(const f32x4*)(Xin32 + p + 4); }
;                     else { acc[ai][bj][m][0] = __builtin_bit_cast(f32x4, *(const u32x4*)(HiIn + p)); acc[ai][bj][m][1] = __builtin_bit_cast(f32x4, *(const u32x4*)(LoIn + p)); } }
	v_cndmask_b32_e64 v51, v9, v5, s[36:37]
	v_cndmask_b32_e64 v50, v8, v4, s[36:37]
	v_lshl_add_u64 v[2:3], s[14:15], 0, v[2:3]
	v_lshl_add_u64 v[4:5], v[6:7], 0, s[16:17]
	v_lshl_add_u64 v[6:7], v[8:9], 0, s[18:19]
	v_lshl_add_u64 v[8:9], v[8:9], 0, s[20:21]
	v_cndmask_b32_e64 v13, v23, v13, s[36:37]
	v_cndmask_b32_e64 v12, v22, v12, s[36:37]
	v_cndmask_b32_e64 v11, v11, v21, s[36:37]
	v_cndmask_b32_e64 v10, v10, v20, s[36:37]
	v_lshl_add_u64 v[18:19], s[14:15], 0, v[18:19]
	v_lshl_add_u64 v[20:21], v[20:21], 0, s[16:17]
	v_lshl_add_u64 v[24:25], v[22:23], 0, s[18:19]
	v_lshl_add_u64 v[22:23], v[22:23], 0, s[20:21]
	v_cndmask_b32_e64 v29, v39, v29, s[36:37]
	v_cndmask_b32_e64 v28, v38, v28, s[36:37]
	v_cndmask_b32_e64 v27, v27, v37, s[36:37]
	v_cndmask_b32_e64 v26, v26, v36, s[36:37]
	v_lshl_add_u64 v[34:35], s[14:15], 0, v[34:35]
	v_lshl_add_u64 v[36:37], v[36:37], 0, s[16:17]
	v_lshl_add_u64 v[40:41], v[38:39], 0, s[18:19]
	v_lshl_add_u64 v[38:39], v[38:39], 0, s[20:21]
	v_lshl_add_u64 v[54:55], s[14:15], 0, v[54:55]
	v_cndmask_b32_e64 v67, v61, v67, s[36:37]
	v_cndmask_b32_e64 v66, v60, v66, s[36:37]
	v_cndmask_b32_e64 v69, v69, v77, s[36:37]
	v_cndmask_b32_e64 v68, v68, v76, s[36:37]
	v_lshl_add_u64 v[74:75], s[14:15], 0, v[74:75]
	v_lshl_add_u64 v[76:77], v[76:77], 0, s[16:17]
	v_lshl_add_u64 v[78:79], v[60:61], 0, s[18:19]
	v_lshl_add_u64 v[60:61], v[60:61], 0, s[20:21]
	v_cndmask_b32_e64 v3, v7, v3, s[36:37]
	v_cndmask_b32_e64 v2, v6, v2, s[36:37]
	v_cndmask_b32_e64 v5, v9, v5, s[36:37]
	v_cndmask_b32_e64 v4, v8, v4, s[36:37]
	v_cndmask_b32_e64 v19, v25, v19, s[36:37]
	v_cndmask_b32_e64 v18, v24, v18, s[36:37]
	v_cndmask_b32_e64 v21, v23, v21, s[36:37]
	v_cndmask_b32_e64 v20, v22, v20, s[36:37]
	v_cndmask_b32_e64 v35, v41, v35, s[36:37]
	v_cndmask_b32_e64 v34, v40, v34, s[36:37]
	v_cndmask_b32_e64 v37, v39, v37, s[36:37]
	v_cndmask_b32_e64 v36, v38, v36, s[36:37]
	v_cndmask_b32_e64 v55, v63, v55, s[36:37]
	v_cndmask_b32_e64 v54, v62, v54, s[36:37]
	v_cndmask_b32_e64 v75, v79, v75, s[36:37]
	v_cndmask_b32_e64 v74, v78, v74, s[36:37]
	v_cndmask_b32_e64 v61, v61, v77, s[36:37]
	v_cndmask_b32_e64 v60, v60, v76, s[36:37]
	s_mov_b64 s[22:23], 0x24000
	global_load_dwordx4 v[6:9], v[2:3], off
	s_nop 0
	global_load_dwordx4 v[2:5], v[4:5], off
	s_nop 0
	global_load_dwordx4 v[14:17], v[12:13], off
	s_nop 0
	global_load_dwordx4 v[10:13], v[10:11], off
	s_nop 0
	global_load_dwordx4 v[22:25], v[18:19], off
	s_nop 0
	global_load_dwordx4 v[18:21], v[20:21], off
	s_nop 0
	global_load_dwordx4 v[30:33], v[28:29], off
	s_nop 0
	global_load_dwordx4 v[26:29], v[26:27], off
	s_nop 0
	global_load_dwordx4 v[38:41], v[34:35], off
	s_nop 0
	global_load_dwordx4 v[34:37], v[36:37], off
	s_nop 0
	global_load_dwordx4 v[46:49], v[44:45], off
	s_nop 0
	global_load_dwordx4 v[42:45], v[42:43], off
	s_nop 0
	global_load_dwordx4 v[62:65], v[54:55], off
	s_nop 0
	global_load_dwordx4 v[54:57], v[56:57], off
	s_nop 0
	global_load_dwordx4 v[70:73], v[66:67], off
	s_nop 0
	global_load_dwordx4 v[66:69], v[68:69], off
	s_nop 0
	global_load_dwordx4 v[78:81], v[74:75], off
	s_nop 0
	global_load_dwordx4 v[74:77], v[60:61], off
	v_lshl_add_u64 v[60:61], v[58:59], 0, s[22:23]
	v_lshlrev_b64 v[90:91], 1, v[60:61]
	v_lshl_add_u64 v[60:61], v[60:61], 2, s[10:11]
	v_lshl_add_u64 v[82:83], s[14:15], 0, v[90:91]
	v_lshl_add_u64 v[92:93], s[50:51], 0, v[90:91]
	v_lshl_add_u64 v[84:85], v[60:61], 0, 16
	v_or_b32_e32 v90, 0x100, v90
	v_cndmask_b32_e64 v83, v61, v83, s[36:37]
	v_cndmask_b32_e64 v82, v60, v82, s[36:37]
	v_cndmask_b32_e64 v85, v85, v93, s[36:37]
	v_cndmask_b32_e64 v84, v84, v92, s[36:37]
	v_lshl_add_u64 v[90:91], s[14:15], 0, v[90:91]
	v_lshl_add_u64 v[92:93], v[92:93], 0, s[16:17]
	v_lshl_add_u64 v[94:95], v[60:61], 0, s[18:19]
	v_lshl_add_u64 v[60:61], v[60:61], 0, s[20:21]
	v_cndmask_b32_e64 v91, v95, v91, s[36:37]
	v_cndmask_b32_e64 v90, v94, v90, s[36:37]
	v_cndmask_b32_e64 v61, v61, v93, s[36:37]
	v_cndmask_b32_e64 v60, v60, v92, s[36:37]
	s_mov_b64 s[22:23], 0x28000
	global_load_dwordx4 v[86:89], v[82:83], off
	s_nop 0
	global_load_dwordx4 v[82:85], v[84:85], off
	s_nop 0
	global_load_dwordx4 v[94:97], v[90:91], off
	s_nop 0
	global_load_dwordx4 v[90:93], v[60:61], off
	v_lshl_add_u64 v[60:61], v[58:59], 0, s[22:23]
	v_lshlrev_b64 v[106:107], 1, v[60:61]
	v_lshl_add_u64 v[60:61], v[60:61], 2, s[10:11]
	v_lshl_add_u64 v[98:99], s[14:15], 0, v[106:107]
	v_lshl_add_u64 v[108:109], s[50:51], 0, v[106:107]
	v_lshl_add_u64 v[100:101], v[60:61], 0, 16
	v_or_b32_e32 v106, 0x100, v106
	v_cndmask_b32_e64 v99, v61, v99, s[36:37]
	v_cndmask_b32_e64 v98, v60, v98, s[36:37]
	v_cndmask_b32_e64 v101, v101, v109, s[36:37]
	v_cndmask_b32_e64 v100, v100, v108, s[36:37]
	v_lshl_add_u64 v[106:107], s[14:15], 0, v[106:107]
	v_lshl_add_u64 v[108:109], v[108:109], 0, s[16:17]
	v_lshl_add_u64 v[110:111], v[60:61], 0, s[18:19]
	v_lshl_add_u64 v[60:61], v[60:61], 0, s[20:21]
	s_mov_b64 s[22:23], 0x2c000
	v_cndmask_b32_e64 v107, v111, v107, s[36:37]
	v_cndmask_b32_e64 v106, v110, v106, s[36:37]
	v_cndmask_b32_e64 v61, v61, v109, s[36:37]
	v_cndmask_b32_e64 v60, v60, v108, s[36:37]
	v_lshl_add_u64 v[58:59], v[58:59], 0, s[22:23]
	global_load_dwordx4 v[102:105], v[98:99], off
	s_nop 0
	global_load_dwordx4 v[98:101], v[100:101], off
	s_nop 0
	global_load_dwordx4 v[110:113], v[106:107], off
	s_nop 0
	global_load_dwordx4 v[106:109], v[60:61], off
	v_lshlrev_b64 v[60:61], 1, v[58:59]
	v_lshl_add_u64 v[58:59], v[58:59], 2, s[10:11]
	v_lshl_add_u64 v[114:115], s[14:15], 0, v[60:61]
	v_lshl_add_u64 v[122:123], s[50:51], 0, v[60:61]
	v_lshl_add_u64 v[116:117], v[58:59], 0, 16
	v_or_b32_e32 v60, 0x100, v60
	v_cndmask_b32_e64 v115, v59, v115, s[36:37]
	v_cndmask_b32_e64 v114, v58, v114, s[36:37]
	v_cndmask_b32_e64 v117, v117, v123, s[36:37]
	v_cndmask_b32_e64 v116, v116, v122, s[36:37]
	v_lshl_add_u64 v[60:61], s[14:15], 0, v[60:61]
	v_lshl_add_u64 v[122:123], v[122:123], 0, s[16:17]
	v_lshl_add_u64 v[124:125], v[58:59], 0, s[18:19]
	v_lshl_add_u64 v[58:59], v[58:59], 0, s[20:21]
	global_load_dwordx4 v[118:121], v[114:115], off
	s_nop 0
	global_load_dwordx4 v[114:117], v[116:117], off
	v_cndmask_b32_e64 v125, v125, v61, s[36:37]
	v_cndmask_b32_e64 v124, v124, v60, s[36:37]
	v_cndmask_b32_e64 v123, v59, v123, s[36:37]
	v_cndmask_b32_e64 v122, v58, v122, s[36:37]
	global_load_dwordx4 v[58:61], v[50:51], off
	global_load_dwordx4 v[126:129], v[124:125], off
	s_nop 0
	global_load_dwordx4 v[50:53], v[52:53], off
	s_nop 0
	global_load_dwordx4 v[122:125], v[122:123], off
	s_and_b64 vcc, exec, s[38:39]
	s_waitcnt vmcnt(3)
	s_waitcnt vmcnt(1)
	s_cbranch_vccnz .LBB0_456
;     __device__ __forceinline__ void settle(f32x4 (&acc)[2][2][4][2]) const { in.settle(acc); }
;     __device__ __forceinline__ void settle(f32x4 (&acc)[2][2][4][2]) const { in.settle(acc); }
;     __device__ __forceinline__ void settle(f32x4 (&acc)[2][2][4][2]) const {
; #pragma unroll
;         for (int a = 0; a < 2; ++a)
; #pragma unroll
;             for (int b = 0; b < 2; ++b)
; #pragma unroll
;                 for (int m = 0; m < 4; ++m) {
;                     asm volatile("" : "+v"(acc[a][b][m][0])); asm volatile("" : "+v"(acc[a][b][m][1]));
;                     if (!Xin32) { const u32x4 h = __builtin_bit_cast(u32x4, acc[a][b][m][0]), l = __builtin_bit_cast(u32x4, acc[a][b][m][1]);
;                         acc[a][b][m][0] = (f32x4){bflo(h.x) + bflo(l.x), bfhi(h.x) + bfhi(l.x), bflo(h.y) + bflo(l.y), bfhi(h.y) + bfhi(l.y)};
;                         acc[a][b][m][1] = (f32x4){bflo(h.z) + bflo(l.z), bfhi(h.z) + bfhi(l.z), bflo(h.w) + bflo(l.w), bfhi(h.w) + bfhi(l.w)}; } }
	v_lshlrev_b32_e32 v130, 16, v58
	v_and_b32_e32 v131, 0xffff0000, v58
	v_lshlrev_b32_e32 v134, 16, v50
	v_and_b32_e32 v135, 0xffff0000, v50
	v_lshlrev_b32_e32 v50, 16, v59
	v_lshlrev_b32_e32 v132, 16, v51
	v_and_b32_e32 v133, 0xffff0000, v51
	v_and_b32_e32 v51, 0xffff0000, v59
	v_pk_add_f32 v[132:133], v[50:51], v[132:133]
	v_pk_add_f32 v[130:131], v[130:131], v[134:135]
	v_lshlrev_b32_e32 v50, 16, v60
	v_and_b32_e32 v51, 0xffff0000, v60
	v_lshlrev_b32_e32 v58, 16, v52
	v_and_b32_e32 v59, 0xffff0000, v52
	v_lshlrev_b32_e32 v52, 16, v61
	v_lshlrev_b32_e32 v134, 16, v53
	v_and_b32_e32 v135, 0xffff0000, v53
	v_and_b32_e32 v53, 0xffff0000, v61
	v_pk_add_f32 v[50:51], v[50:51], v[58:59]
	v_mov_b64_e32 v[58:59], v[130:131]
	v_pk_add_f32 v[52:53], v[52:53], v[134:135]
	v_mov_b64_e32 v[60:61], v[132:133]
